# NSA score tiles: fixed softmax reference -16.0 folded into the MFMA C operand (108 v_add removed per 4 loops), wait states re-derived
# baseline (speedup 1.0000x reference)
.LBB0_375:
	s_or_b64 exec, exec, s[6:7]
	v_readfirstlane_b32 s1, v0
	s_cmpk_gt_u32 s1, 0x1ff
	s_mov_b64 s[6:7], -1
	s_cbranch_scc1 .LBB0_370
	v_mov_b32_e32 v244, 0xc1800000
	v_mov_b32_e32 v245, v244
	v_mov_b32_e32 v246, v244
	v_mov_b32_e32 v247, v244
	s_lshl_b32 s0, s1, 4
	s_and_b32 s0, s0, 0xff0
	v_mov_b32_e32 v152, v182
	s_xor_b32 s80, s0, 0xff0
	v_and_b32_e32 v128, 15, v152
	v_or_b32_e32 v134, s80, v128
	v_ashrrev_i32_e32 v168, 4, v152
	v_or_b32_e32 v169, s97, v134
	v_mov_b64_e32 v[0:1], s[34:35]
	v_mad_u64_u32 v[136:137], s[6:7], v169, s89, v[0:1]
	v_lshlrev_b32_e32 v130, 3, v168
	v_ashrrev_i32_e32 v131, 31, v130
	s_and_b32 s6, s1, 0x100
	v_lshl_add_u64 v[8:9], v[130:131], 1, v[136:137]
	s_lshl_b32 s70, s6, 1
	s_mov_b32 s71, s49
	v_lshl_add_u64 v[4:5], v[8:9], 0, s[70:71]
	global_load_dwordx4 v[0:3], v[4:5], off
	s_nop 0
	global_load_dwordx4 v[4:7], v[4:5], off offset:64
	s_lshr_b32 s22, s1, 8
	s_lshl_b32 s1, s22, 2
	s_or_b32 s6, s1, 1
	s_lshl_b32 s48, s6, 7
	v_lshl_add_u64 v[14:15], v[8:9], 0, s[48:49]
	global_load_dwordx4 v[10:13], v[14:15], off
	s_nop 0
	global_load_dwordx4 v[14:17], v[14:15], off offset:64
	v_lshl_add_u64 v[18:19], v[130:131], 2, s[42:43]
	global_load_dwordx4 v[36:39], v[18:19], off
	global_load_dwordx4 v[32:35], v[18:19], off offset:128
	global_load_dwordx4 v[28:31], v[18:19], off offset:16
	global_load_dwordx4 v[24:27], v[18:19], off offset:144
	v_cmp_lt_i32_e32 vcc, v162, v163
	s_or_b32 s7, s1, 2
	s_lshl_b32 s48, s7, 7
	v_cndmask_b32_e32 v18, v181, v162, vcc
	v_lshlrev_b32_e32 v167, 2, v18
	v_cmp_lt_i32_e32 vcc, v164, v163
	s_or_b32 s8, s1, 3
	s_add_i32 s1, s1, 4
	v_mov_b32_e32 v129, 0
	v_lshl_add_u32 v131, v152, 2, s79
	v_and_b32_e32 v138, -16, v152
	v_lshlrev_b32_e32 v132, 4, v128
	s_mul_i32 s74, s22, 24
	s_mul_i32 s72, s6, 6
	v_ashrrev_i32_e32 v139, 31, v138
	v_mov_b32_e32 v189, 0
	v_mov_b32_e32 v187, 0
	v_mov_b32_e32 v188, 0
	v_mov_b32_e32 v157, 0
	v_mov_b32_e32 v158, 0
	v_mov_b32_e32 v156, 0
	v_mov_b32_e32 v155, 0
	v_mov_b32_e32 v190, 0
	v_mov_b32_e32 v191, 0
	v_mov_b32_e32 v185, 0
	v_mov_b32_e32 v186, 0
	v_mov_b32_e32 v159, 0
	v_mov_b32_e32 v160, 0
	v_mov_b32_e32 v154, 0
	v_mov_b32_e32 v153, 0
	v_mov_b32_e32 v192, 0
	v_mov_b32_e32 v193, 0
	v_mov_b32_e32 v178, 0
	v_mov_b32_e32 v179, 0
	v_mov_b32_e32 v161, 0
	v_mov_b32_e32 v174, 0
	v_mov_b32_e32 v151, 0
	v_mov_b32_e32 v150, 0
	v_mov_b32_e32 v194, 0
	v_mov_b32_e32 v195, 0
	v_mov_b32_e32 v177, 0
	v_mov_b32_e32 v184, 0
	v_mov_b32_e32 v175, 0
	v_mov_b32_e32 v176, 0
	v_mov_b32_e32 v149, 0
	v_mov_b32_e32 v148, 0
	s_waitcnt vmcnt(7)
	v_lshlrev_b32_e32 v18, 16, v0
	s_waitcnt vmcnt(6)
	v_lshlrev_b32_e32 v20, 16, v4
	v_and_b32_e32 v21, 0xffff0000, v4
	v_and_b32_e32 v19, 0xffff0000, v0
	v_and_b32_e32 v4, 0xffff0000, v5
	v_lshlrev_b32_e32 v5, 16, v5
	v_pk_mul_f32 v[42:43], v[20:21], v[20:21]
	v_and_b32_e32 v0, 0xffff0000, v1
	v_lshlrev_b32_e32 v1, 16, v1
	v_pk_mul_f32 v[44:45], v[4:5], v[4:5]
	v_pk_fma_f32 v[42:43], v[18:19], v[18:19], v[42:43]
	v_and_b32_e32 v40, 0xffff0000, v6
	v_lshlrev_b32_e32 v41, 16, v6
	v_pk_fma_f32 v[44:45], v[0:1], v[0:1], v[44:45]
	v_add_f32_e32 v42, v42, v43
	v_and_b32_e32 v22, 0xffff0000, v2
	v_lshlrev_b32_e32 v23, 16, v2
	v_pk_mul_f32 v[46:47], v[40:41], v[40:41]
	v_add_f32_e32 v42, v45, v42
	v_and_b32_e32 v6, 0xffff0000, v7
	v_lshlrev_b32_e32 v7, 16, v7
	v_pk_fma_f32 v[46:47], v[22:23], v[22:23], v[46:47]
	v_add_f32_e32 v42, v44, v42
	v_and_b32_e32 v2, 0xffff0000, v3
	v_lshlrev_b32_e32 v3, 16, v3
	v_pk_mul_f32 v[48:49], v[6:7], v[6:7]
	v_add_f32_e32 v42, v47, v42
	v_pk_fma_f32 v[48:49], v[2:3], v[2:3], v[48:49]
	v_add_f32_e32 v42, v46, v42
	v_add_f32_e32 v42, v49, v42
	v_add_f32_e32 v42, v48, v42
	ds_bpermute_b32 v43, v167, v42
	v_cndmask_b32_e32 v44, v181, v164, vcc
	v_lshlrev_b32_e32 v166, 2, v44
	s_waitcnt vmcnt(5)
	v_lshlrev_b32_e32 v44, 16, v10
	v_and_b32_e32 v45, 0xffff0000, v10
	s_waitcnt lgkmcnt(0)
	v_add_f32_e32 v42, v42, v43
	ds_bpermute_b32 v43, v166, v42
	s_waitcnt vmcnt(4)
	v_lshlrev_b32_e32 v46, 16, v14
	v_and_b32_e32 v47, 0xffff0000, v14
	s_waitcnt lgkmcnt(0)
	v_add_f32_e32 v10, v42, v43
	v_fmamk_f32 v10, v10, 0x3c800000, v135
	v_mul_f32_e32 v14, 0x4b800000, v10
	v_cmp_gt_f32_e32 vcc, s90, v10
	v_pk_mul_f32 v[42:43], v[46:47], v[46:47]
	s_nop 0
	v_cndmask_b32_e32 v10, v10, v14, vcc
	v_rsq_f32_e32 v14, v10
	v_pk_fma_f32 v[48:49], v[44:45], v[44:45], v[42:43]
	v_and_b32_e32 v10, 0xffff0000, v11
	v_lshlrev_b32_e32 v11, 16, v11
	v_mul_f32_e32 v42, 0x45800000, v14
	v_cndmask_b32_e32 v14, v14, v42, vcc
	v_mul_f32_e32 v14, 0x3e38aa3b, v14
	s_waitcnt vmcnt(3)
	v_mul_f32_e32 v52, v38, v14
	v_mul_f32_e32 v54, v39, v14
	v_mul_f32_e32 v42, v36, v14
	s_waitcnt vmcnt(2)
	v_mul_f32_e32 v43, v32, v14
	v_mul_f32_e32 v50, v37, v14
	v_mul_f32_e32 v51, v33, v14
	v_mul_f32_e32 v52, v52, v1
	v_mul_f32_e32 v54, v54, v0
	v_lshl_add_u64 v[0:1], v[8:9], 0, s[48:49]
	v_mul_f32_e32 v63, v42, v18
	v_mul_f32_e32 v64, v43, v20
	v_mul_f32_e32 v65, v50, v19
	v_mul_f32_e32 v66, v51, v21
	global_load_dwordx4 v[18:21], v[0:1], off
	s_waitcnt vmcnt(1)
	v_mul_f32_e32 v57, v24, v14
	v_mul_f32_e32 v59, v25, v14
	v_mul_f32_e32 v53, v34, v14
	v_mul_f32_e32 v55, v35, v14
	v_mul_f32_e32 v56, v28, v14
	v_mul_f32_e32 v58, v29, v14
	v_mul_f32_e32 v60, v30, v14
	v_mul_f32_e32 v61, v26, v14
	v_mul_f32_e32 v62, v31, v14
	v_mul_f32_e32 v14, v27, v14
	v_mul_f32_e32 v57, v57, v41
	v_mul_f32_e32 v59, v59, v40
	global_load_dwordx4 v[40:43], v[0:1], off offset:64
	v_mul_f32_e32 v7, v61, v7
	v_mul_f32_e32 v61, v62, v2
	v_mul_f32_e32 v62, v14, v6
	v_and_b32_e32 v14, 0xffff0000, v15
	v_lshlrev_b32_e32 v15, 16, v15
	v_pk_mul_f32 v[0:1], v[14:15], v[14:15]
	v_and_b32_e32 v50, 0xffff0000, v16
	v_pk_fma_f32 v[0:1], v[10:11], v[10:11], v[0:1]
	v_lshlrev_b32_e32 v51, 16, v16
	v_add_f32_e32 v6, v48, v49
	v_mul_f32_e32 v56, v56, v23
	v_mul_f32_e32 v58, v58, v22
	v_mul_f32_e32 v60, v60, v3
	v_and_b32_e32 v22, 0xffff0000, v12
	v_lshlrev_b32_e32 v23, 16, v12
	v_pk_mul_f32 v[2:3], v[50:51], v[50:51]
	v_add_f32_e32 v1, v1, v6
	v_pk_fma_f32 v[2:3], v[22:23], v[22:23], v[2:3]
	v_and_b32_e32 v16, 0xffff0000, v17
	v_lshlrev_b32_e32 v17, 16, v17
	v_add_f32_e32 v0, v0, v1
	v_mul_f32_e32 v53, v53, v5
	v_mul_f32_e32 v55, v55, v4
	v_and_b32_e32 v12, 0xffff0000, v13
	v_lshlrev_b32_e32 v13, 16, v13
	v_pk_mul_f32 v[4:5], v[16:17], v[16:17]
	v_add_f32_e32 v0, v3, v0
	v_pk_fma_f32 v[4:5], v[12:13], v[12:13], v[4:5]
	v_add_f32_e32 v0, v2, v0
	v_add_f32_e32 v0, v5, v0
	v_add_f32_e32 v3, v4, v0
	ds_bpermute_b32 v4, v167, v3
	v_cvt_f32_u32_e32 v6, s6
	v_cvt_pk_bf16_f32 v1, v52, v54
	v_cvt_pk_bf16_f32 v2, v56, v58
	v_cvt_pk_bf16_f32 v7, v7, v62
	s_waitcnt lgkmcnt(0)
	v_add_f32_e32 v48, v3, v4
	ds_bpermute_b32 v49, v166, v48
	v_exp_f32_e64 v52, -v6
	v_cvt_pk_bf16_f32 v3, v60, v61
	v_cvt_pk_bf16_f32 v0, v63, v65
	v_cvt_pk_bf16_f32 v4, v64, v66
	s_waitcnt lgkmcnt(0)
	v_add_f32_e32 v6, v48, v49
	v_fmamk_f32 v6, v6, 0x3c800000, v135
	v_mul_f32_e32 v48, 0x4b800000, v6
	v_cmp_gt_f32_e32 vcc, s90, v6
	s_lshl_b32 s48, s8, 7
	v_lshl_add_u64 v[8:9], v[8:9], 0, s[48:49]
	v_cndmask_b32_e32 v6, v6, v48, vcc
	v_rsq_f32_e32 v48, v6
	v_cvt_pk_bf16_f32 v6, v57, v59
	v_cvt_pk_bf16_f32 v5, v53, v55
	v_mul_f32_e32 v170, 0x3fb8aa3b, v52
	v_mul_f32_e32 v49, 0x45800000, v48
	v_cndmask_b32_e32 v48, v48, v49, vcc
	v_mul_f32_e32 v48, 0x3e38aa3b, v48
	v_mul_f32_e32 v49, v36, v48
	v_mul_f32_e32 v56, v49, v44
	v_mul_f32_e32 v44, v32, v48
	v_mul_f32_e32 v57, v44, v46
	v_mul_f32_e32 v44, v37, v48
	v_mul_f32_e32 v58, v44, v45
	v_mul_f32_e32 v44, v33, v48
	v_mul_f32_e32 v59, v44, v47
	v_mul_f32_e32 v44, v38, v48
	v_mul_f32_e32 v60, v44, v11
	v_mul_f32_e32 v11, v34, v48
	v_mul_f32_e32 v61, v11, v15
	v_mul_f32_e32 v11, v39, v48
	v_mul_f32_e32 v62, v11, v10
	v_mul_f32_e32 v10, v35, v48
	v_mul_f32_e32 v63, v10, v14
	v_mul_f32_e32 v10, v28, v48
	v_mul_f32_e32 v64, v10, v23
	v_mul_f32_e32 v10, v24, v48
	v_mul_f32_e32 v65, v10, v51
	v_mul_f32_e32 v10, v29, v48
	v_mul_f32_e32 v66, v10, v22
	v_mul_f32_e32 v10, v25, v48
	v_mul_f32_e32 v67, v10, v50
	v_mul_f32_e32 v10, v30, v48
	v_mul_f32_e32 v68, v10, v13
	v_mul_f32_e32 v10, v26, v48
	v_mul_f32_e32 v69, v10, v17
	v_mul_f32_e32 v10, v31, v48
	v_mul_f32_e32 v70, v10, v12
	v_mul_f32_e32 v10, v27, v48
	v_mul_f32_e32 v71, v10, v16
	s_waitcnt vmcnt(1)
	v_lshlrev_b32_e32 v22, 16, v18
	v_and_b32_e32 v23, 0xffff0000, v18
	v_and_b32_e32 v50, 0xffff0000, v19
	v_lshlrev_b32_e32 v51, 16, v19
	global_load_dwordx4 v[16:19], v[8:9], off
	global_load_dwordx4 v[44:47], v[8:9], off offset:64
	s_waitcnt vmcnt(2)
	v_lshlrev_b32_e32 v48, 16, v40
	v_and_b32_e32 v49, 0xffff0000, v40
	v_pk_mul_f32 v[10:11], v[48:49], v[48:49]
	v_and_b32_e32 v40, 0xffff0000, v41
	v_lshlrev_b32_e32 v41, 16, v41
	v_pk_fma_f32 v[10:11], v[22:23], v[22:23], v[10:11]
	v_pk_mul_f32 v[8:9], v[40:41], v[40:41]
	v_and_b32_e32 v54, 0xffff0000, v42
	v_pk_fma_f32 v[8:9], v[50:51], v[50:51], v[8:9]
	v_lshlrev_b32_e32 v55, 16, v42
	v_add_f32_e32 v10, v10, v11
	v_and_b32_e32 v52, 0xffff0000, v20
	v_lshlrev_b32_e32 v53, 16, v20
	v_pk_mul_f32 v[12:13], v[54:55], v[54:55]
	v_add_f32_e32 v9, v9, v10
	v_pk_fma_f32 v[12:13], v[52:53], v[52:53], v[12:13]
	v_and_b32_e32 v42, 0xffff0000, v43
	v_lshlrev_b32_e32 v43, 16, v43
	v_add_f32_e32 v8, v8, v9
	v_and_b32_e32 v20, 0xffff0000, v21
	v_lshlrev_b32_e32 v21, 16, v21
	v_pk_mul_f32 v[14:15], v[42:43], v[42:43]
	v_add_f32_e32 v8, v13, v8
	v_pk_fma_f32 v[14:15], v[20:21], v[20:21], v[14:15]
	v_add_f32_e32 v8, v12, v8
	v_add_f32_e32 v8, v15, v8
	v_add_f32_e32 v11, v14, v8
	ds_bpermute_b32 v12, v167, v11
	v_cvt_pk_bf16_f32 v8, v56, v58
	v_cvt_f32_u32_e32 v14, s7
	v_cvt_pk_bf16_f32 v9, v60, v62
	v_cvt_pk_bf16_f32 v13, v61, v63
	s_waitcnt lgkmcnt(0)
	v_add_f32_e32 v15, v11, v12
	ds_bpermute_b32 v56, v166, v15
	v_cvt_pk_bf16_f32 v12, v57, v59
	v_exp_f32_e64 v57, -v14
	v_cvt_pk_bf16_f32 v10, v64, v66
	v_cvt_pk_bf16_f32 v11, v68, v70
	s_waitcnt lgkmcnt(0)
	v_add_f32_e32 v14, v15, v56
	v_fmamk_f32 v14, v14, 0x3c800000, v135
	v_mul_f32_e32 v15, 0x4b800000, v14
	v_cmp_gt_f32_e32 vcc, s90, v14
	v_mul_f32_e32 v171, 0x3fb8aa3b, v57
	ds_write2st64_b32 v131, v129, v129 offset1:1
	ds_write2st64_b32 v131, v129, v129 offset0:2 offset1:3
	ds_write2st64_b32 v131, v129, v129 offset0:4 offset1:5
	ds_write2st64_b32 v131, v129, v129 offset0:6 offset1:7
	ds_write2st64_b32 v131, v129, v129 offset0:8 offset1:9
	ds_write2st64_b32 v131, v129, v129 offset0:10 offset1:11
	ds_write2st64_b32 v131, v129, v129 offset0:12 offset1:13
	ds_write2st64_b32 v131, v129, v129 offset0:14 offset1:15
	v_cndmask_b32_e32 v14, v14, v15, vcc
	v_rsq_f32_e32 v56, v14
	v_cvt_pk_bf16_f32 v14, v65, v67
	v_cvt_pk_bf16_f32 v15, v69, v71
	s_waitcnt lgkmcnt(0)
	s_cmpk_eq_i32 s0, 0xff0
	v_mul_f32_e32 v57, 0x45800000, v56
	v_cndmask_b32_e32 v56, v56, v57, vcc
	v_mul_f32_e32 v56, 0x3e38aa3b, v56
	v_mul_f32_e32 v57, v36, v56
	v_mul_f32_e32 v57, v57, v22
	v_mul_f32_e32 v22, v32, v56
	v_mul_f32_e32 v58, v22, v48
	v_mul_f32_e32 v22, v37, v56
	v_mul_f32_e32 v59, v22, v23
	v_mul_f32_e32 v22, v33, v56
	v_mul_f32_e32 v60, v22, v49
	v_mul_f32_e32 v22, v38, v56
	v_mul_f32_e32 v61, v22, v51
	v_mul_f32_e32 v22, v34, v56
	v_mul_f32_e32 v62, v22, v41
	v_mul_f32_e32 v22, v39, v56
	v_mul_f32_e32 v63, v22, v50
	v_mul_f32_e32 v22, v35, v56
	v_mul_f32_e32 v64, v22, v40
	v_mul_f32_e32 v22, v28, v56
	v_mul_f32_e32 v65, v22, v53
	v_mul_f32_e32 v22, v24, v56
	v_mul_f32_e32 v66, v22, v55
	v_mul_f32_e32 v22, v29, v56
	v_mul_f32_e32 v67, v22, v52
	v_mul_f32_e32 v22, v25, v56
	v_mul_f32_e32 v68, v22, v54
	v_mul_f32_e32 v22, v30, v56
	v_mul_f32_e32 v69, v22, v21
	v_mul_f32_e32 v21, v26, v56
	v_mul_f32_e32 v70, v21, v43
	v_mul_f32_e32 v21, v31, v56
	v_mul_f32_e32 v71, v21, v20
	v_mul_f32_e32 v20, v27, v56
	v_mul_f32_e32 v56, v20, v42
	s_waitcnt vmcnt(0)
	v_lshlrev_b32_e32 v42, 16, v44
	v_and_b32_e32 v43, 0xffff0000, v44
	v_lshlrev_b32_e32 v40, 16, v16
	v_and_b32_e32 v41, 0xffff0000, v16
	v_pk_mul_f32 v[20:21], v[42:43], v[42:43]
	v_and_b32_e32 v44, 0xffff0000, v45
	v_lshlrev_b32_e32 v45, 16, v45
	v_pk_fma_f32 v[20:21], v[40:41], v[40:41], v[20:21]
	v_and_b32_e32 v48, 0xffff0000, v17
	v_lshlrev_b32_e32 v49, 16, v17
	v_pk_mul_f32 v[16:17], v[44:45], v[44:45]
	v_and_b32_e32 v52, 0xffff0000, v46
	v_pk_fma_f32 v[16:17], v[48:49], v[48:49], v[16:17]
	v_lshlrev_b32_e32 v53, 16, v46
	v_add_f32_e32 v20, v20, v21
	v_and_b32_e32 v50, 0xffff0000, v18
	v_lshlrev_b32_e32 v51, 16, v18
	v_pk_mul_f32 v[22:23], v[52:53], v[52:53]
	v_add_f32_e32 v17, v17, v20
	v_pk_fma_f32 v[22:23], v[50:51], v[50:51], v[22:23]
	v_and_b32_e32 v46, 0xffff0000, v47
	v_lshlrev_b32_e32 v47, 16, v47
	v_add_f32_e32 v16, v16, v17
	v_and_b32_e32 v54, 0xffff0000, v19
	v_lshlrev_b32_e32 v55, 16, v19
	v_pk_mul_f32 v[18:19], v[46:47], v[46:47]
	v_add_f32_e32 v16, v23, v16
	v_pk_fma_f32 v[18:19], v[54:55], v[54:55], v[18:19]
	v_add_f32_e32 v16, v22, v16
	v_add_f32_e32 v16, v19, v16
	v_add_f32_e32 v19, v18, v16
	ds_bpermute_b32 v20, v167, v19
	v_cvt_pk_bf16_f32 v16, v57, v59
	v_cvt_f32_u32_e32 v22, s8
	v_cvt_pk_bf16_f32 v17, v61, v63
	v_cvt_pk_bf16_f32 v18, v65, v67
	s_waitcnt lgkmcnt(0)
	v_add_f32_e32 v23, v19, v20
	ds_bpermute_b32 v57, v166, v23
	v_cvt_pk_bf16_f32 v20, v58, v60
	v_exp_f32_e64 v58, -v22
	v_cvt_pk_bf16_f32 v19, v69, v71
	v_cvt_pk_bf16_f32 v21, v62, v64
	s_waitcnt lgkmcnt(0)
	v_add_f32_e32 v22, v23, v57
	v_fmamk_f32 v22, v22, 0x3c800000, v135
	v_mul_f32_e32 v23, 0x4b800000, v22
	v_cmp_gt_f32_e32 vcc, s90, v22
	v_mul_f32_e32 v172, 0x3fb8aa3b, v58
	s_nop 0
	v_cndmask_b32_e32 v22, v22, v23, vcc
	v_rsq_f32_e32 v57, v22
	v_cvt_pk_bf16_f32 v23, v70, v56
	v_cvt_pk_bf16_f32 v22, v66, v68
	s_nop 0
	v_mul_f32_e32 v56, 0x45800000, v57
	v_cndmask_b32_e32 v56, v57, v56, vcc
	v_mul_f32_e32 v56, 0x3e38aa3b, v56
	v_mul_f32_e32 v36, v36, v56
	v_mul_f32_e32 v24, v24, v56
	v_mul_f32_e32 v36, v36, v40
	v_mul_f32_e32 v40, v24, v53
	v_mul_f32_e32 v24, v29, v56
	v_mul_f32_e32 v37, v37, v56
	v_mul_f32_e32 v29, v24, v50
	v_mul_f32_e32 v24, v25, v56
	v_mul_f32_e32 v37, v37, v41
	v_mul_f32_e32 v41, v24, v52
	v_mul_f32_e32 v24, v30, v56
	v_mul_f32_e32 v32, v32, v56
	v_mul_f32_e32 v30, v24, v55
	v_mul_f32_e32 v24, v26, v56
	v_mul_f32_e32 v32, v32, v42
	v_mul_f32_e32 v42, v24, v47
	v_mul_f32_e32 v24, v31, v56
	v_mul_f32_e32 v33, v33, v56
	v_mul_f32_e32 v31, v24, v54
	v_mul_f32_e32 v24, v27, v56
	v_mul_f32_e32 v33, v33, v43
	v_mul_f32_e32 v43, v24, v46
	v_cvt_pk_bf16_f32 v24, v36, v37
	v_cvt_f32_u32_e32 v36, s1
	v_mul_f32_e32 v28, v28, v56
	v_mul_f32_e32 v28, v28, v51
	v_cvt_pk_bf16_f32 v26, v28, v29
	v_cvt_pk_bf16_f32 v28, v32, v33
	v_exp_f32_e64 v32, -v36
	v_mul_f32_e32 v38, v38, v56
	v_mul_f32_e32 v34, v34, v56
	v_mul_f32_e32 v39, v39, v56
	v_mul_f32_e32 v35, v35, v56
	v_mul_f32_e32 v173, 0x3fb8aa3b, v32
	v_mul_f32_e32 v38, v38, v49
	v_mul_f32_e32 v34, v34, v45
	v_mul_f32_e32 v39, v39, v48
	v_mul_f32_e32 v35, v35, v44
	v_cvt_pk_bf16_f32 v25, v38, v39
	v_cvt_pk_bf16_f32 v27, v30, v31
	v_cvt_pk_bf16_f32 v29, v34, v35
	v_cvt_pk_bf16_f32 v30, v40, v41
	v_cvt_pk_bf16_f32 v31, v42, v43
	s_cbranch_scc1 .LBB0_386
	s_or_b32 s1, s22, s96
	s_lshr_b32 s0, s0, 4
	s_lshl_b32 s1, s1, 15
	s_sub_i32 s0, 0x11e, s0
	s_add_u32 s6, s83, s1
	s_addc_u32 s7, s84, 0
	v_lshl_add_u64 v[32:33], v[138:139], 4, s[6:7]
	s_add_i32 s6, s80, 0xffffff71
	v_lshl_add_u64 v[140:141], v[32:33], 0, v[132:133]
	v_lshlrev_b32_e32 v153, 7, v168
	v_add_u32_e32 v32, s6, v128
	s_lshr_b32 s0, s0, 5
	v_sub_u32_e32 v154, v32, v153
	v_add_u32_e32 v36, 0x8f, v153
	v_mov_b32_e32 v33, 0
	s_mov_b32 s18, 2
	v_mov_b32_e32 v37, v154
	s_mov_b32 s20, s0
	v_mov_b32_e32 v34, 0
	v_mov_b32_e32 v32, 0
	v_mov_b32_e32 v35, 0
.LBB0_378:
	s_ashr_i32 s19, s18, 31
	s_lshl_b64 s[6:7], s[18:19], 10
	v_lshl_add_u64 v[42:43], v[140:141], 0, s[6:7]
	s_add_i32 s6, s18, -2
	s_ashr_i32 s7, s6, 31
	s_lshl_b64 s[6:7], s[6:7], 10
	v_lshl_add_u64 v[62:63], v[140:141], 0, s[6:7]
	global_load_dwordx4 v[38:41], v[42:43], off
	s_nop 0
	global_load_dwordx4 v[42:45], v[42:43], off offset:1024
	v_add_u32_e32 v79, 0x70, v37
	global_load_dwordx4 v[58:61], v[62:63], off
	v_add_u32_e32 v87, 48, v37
	global_load_dwordx4 v[62:65], v[62:63], off offset:1024
	v_add_u32_e32 v81, 0x60, v37
	v_cvt_f32_i32_e32 v79, v79
	v_cvt_f32_i32_e32 v87, v87
	v_add_u32_e32 v83, 0x50, v37
	v_cvt_f32_i32_e32 v81, v81
	v_add_u32_e32 v85, 64, v37
	v_cvt_f32_i32_e32 v83, v83
	v_cvt_f32_i32_e32 v85, v85
	v_add_u32_e32 v89, 32, v37
	v_add_u32_e32 v91, 16, v37
	v_cvt_f32_i32_e32 v89, v89
	v_subrev_u32_e32 v86, 48, v36
	v_cvt_f32_i32_e32 v92, v37
	v_add_u32_e32 v78, 0xffffff90, v36
	v_add_u32_e32 v80, 0xffffffa0, v36
	v_cmp_gt_i32_e32 vcc, v86, v134
	v_add_u32_e32 v82, 0xffffffb0, v36
	v_cmp_gt_i32_e64 s[12:13], v80, v134
	v_subrev_u32_e32 v84, 64, v36
	v_cmp_gt_i32_e64 s[14:15], v82, v134
	v_cmp_gt_i32_e64 s[16:17], v84, v134
	v_subrev_u32_e32 v88, 32, v36
	v_add_u32_e32 v90, -16, v36
	v_cmp_gt_i32_e64 s[6:7], v88, v134
	v_cmp_gt_i32_e64 s[8:9], v90, v134
	v_cmp_gt_i32_e64 s[10:11], v36, v134
	s_add_i32 s20, s20, -1
	s_add_i32 s18, s18, 4
	v_add_u32_e32 v37, 0xfffffe00, v37
	s_cmp_lg_u32 s20, 0
	v_add_u32_e32 v36, 0x200, v36
	s_waitcnt vmcnt(3)
	v_mfma_f32_16x16x32_bf16 v[46:49], v[38:41], v[0:3], v[244:247]
	v_mfma_f32_16x16x32_bf16 v[50:53], v[38:41], v[8:11], v[244:247]
	v_mfma_f32_16x16x32_bf16 v[54:57], v[38:41], v[16:19], v[244:247]
	v_mfma_f32_16x16x32_bf16 v[38:41], v[38:41], v[24:27], v[244:247]
	s_waitcnt vmcnt(1)
	v_mfma_f32_16x16x32_bf16 v[66:69], v[58:61], v[0:3], v[244:247]
	v_mfma_f32_16x16x32_bf16 v[70:73], v[58:61], v[8:11], v[244:247]
	v_mfma_f32_16x16x32_bf16 v[74:77], v[58:61], v[16:19], v[244:247]
	v_mfma_f32_16x16x32_bf16 v[58:61], v[58:61], v[24:27], v[244:247]
	v_mfma_f32_16x16x32_bf16 v[46:49], v[42:45], v[4:7], v[46:49]
	v_mfma_f32_16x16x32_bf16 v[50:53], v[42:45], v[12:15], v[50:53]
	v_mfma_f32_16x16x32_bf16 v[54:57], v[42:45], v[20:23], v[54:57]
	s_nop 5
	v_fma_f32 v46, -v170, v87, v46
	v_mfma_f32_16x16x32_bf16 v[38:41], v[42:45], v[28:31], v[38:41]
	v_fma_f32 v50, -v171, v87, v50
	v_fma_f32 v54, -v172, v87, v54
	s_waitcnt vmcnt(0)
	v_mfma_f32_16x16x32_bf16 v[42:45], v[62:65], v[4:7], v[66:69]
	v_exp_f32_e32 v46, v46
	s_nop 1
	s_nop 0
	v_fma_f32 v38, -v173, v87, v38
	v_mfma_f32_16x16x32_bf16 v[66:69], v[62:65], v[12:15], v[70:73]
	v_exp_f32_e32 v50, v50
	s_nop 0
	v_mfma_f32_16x16x32_bf16 v[70:73], v[62:65], v[20:23], v[74:77]
	v_fma_f32 v42, -v170, v79, v42
	v_fma_f32 v43, -v170, v81, v43
	v_mfma_f32_16x16x32_bf16 v[58:61], v[62:65], v[28:31], v[58:61]
	s_nop 1
	v_mov_b32_e32 v62, v66
	s_nop 2
	v_mov_b32_e32 v63, v67
	v_fma_f32 v62, -v171, v79, v62
	v_fma_f32 v66, -v172, v79, v70
	v_fma_f32 v58, -v173, v79, v58
	v_mov_b32_e32 v64, v68
	v_fma_f32 v63, -v171, v81, v63
	v_fma_f32 v67, -v172, v81, v71
	v_exp_f32_e32 v54, v54
	v_fma_f32 v59, -v173, v81, v59
	v_exp_f32_e32 v38, v38
	v_exp_f32_e32 v42, v42
	v_exp_f32_e32 v62, v62
	v_exp_f32_e32 v66, v66
	v_exp_f32_e32 v58, v58
	v_cvt_f32_i32_e32 v74, v91
	v_mov_b32_e32 v65, v69
	v_fma_f32 v44, -v170, v83, v44
	v_fma_f32 v64, -v171, v83, v64
	v_fma_f32 v68, -v172, v83, v72
	v_fma_f32 v60, -v173, v83, v60
	v_exp_f32_e32 v43, v43
	v_exp_f32_e32 v63, v63
	v_exp_f32_e32 v67, v67
	v_exp_f32_e32 v59, v59
	v_fma_f32 v45, -v170, v85, v45
	v_fma_f32 v65, -v171, v85, v65
	v_fma_f32 v69, -v172, v85, v73
	v_fma_f32 v61, -v173, v85, v61
	v_exp_f32_e32 v44, v44
	v_exp_f32_e32 v64, v64
	v_exp_f32_e32 v68, v68
	v_exp_f32_e32 v60, v60
	v_exp_f32_e32 v45, v45
	v_exp_f32_e32 v65, v65
	v_exp_f32_e32 v69, v69
	v_exp_f32_e32 v61, v61
	v_fma_f32 v47, -v170, v89, v47
	v_fma_f32 v51, -v171, v89, v51
	v_fma_f32 v55, -v172, v89, v55
	v_fma_f32 v39, -v173, v89, v39
	v_cndmask_b32_e64 v46, v46, 0, vcc
	v_cndmask_b32_e64 v50, v50, 0, vcc
	v_cndmask_b32_e64 v54, v54, 0, vcc
	v_cndmask_b32_e64 v38, v38, 0, vcc
	v_add_f32_e32 v42, 0, v42
	v_add_f32_e32 v62, 0, v62
	v_add_f32_e32 v66, 0, v66
	v_add_f32_e32 v58, 0, v58
	v_cmp_gt_i32_e32 vcc, v78, v134
	v_fma_f32 v48, -v170, v74, v48
	v_fma_f32 v52, -v171, v74, v52
	v_fma_f32 v56, -v172, v74, v56
	v_fma_f32 v40, -v173, v74, v40
	v_exp_f32_e32 v47, v47
	v_exp_f32_e32 v51, v51
	v_exp_f32_e32 v55, v55
	v_exp_f32_e32 v39, v39
	v_cndmask_b32_e64 v43, v43, 0, s[12:13]
	v_cndmask_b32_e64 v63, v63, 0, s[12:13]
	v_cndmask_b32_e64 v67, v67, 0, s[12:13]
	v_cndmask_b32_e64 v59, v59, 0, s[12:13]
	v_cndmask_b32_e64 v42, v42, 0, vcc
	v_cndmask_b32_e64 v62, v62, 0, vcc
	v_cndmask_b32_e64 v66, v66, 0, vcc
	v_cndmask_b32_e64 v58, v58, 0, vcc
	v_fma_f32 v49, -v170, v92, v49
	v_fma_f32 v53, -v171, v92, v53
	v_fma_f32 v57, -v172, v92, v57
	v_fma_f32 v41, -v173, v92, v41
	v_exp_f32_e32 v48, v48
	v_exp_f32_e32 v52, v52
	v_exp_f32_e32 v56, v56
	v_exp_f32_e32 v40, v40
	v_cndmask_b32_e64 v44, v44, 0, s[14:15]
	v_cndmask_b32_e64 v64, v64, 0, s[14:15]
	v_cndmask_b32_e64 v68, v68, 0, s[14:15]
	v_cndmask_b32_e64 v60, v60, 0, s[14:15]
	v_add_f32_e32 v42, v43, v42
	v_add_f32_e32 v43, v63, v62
	v_add_f32_e32 v62, v67, v66
	v_add_f32_e32 v58, v59, v58
	v_exp_f32_e32 v49, v49
	v_exp_f32_e32 v53, v53
	v_exp_f32_e32 v57, v57
	v_exp_f32_e32 v41, v41
	v_cndmask_b32_e64 v45, v45, 0, s[16:17]
	v_cndmask_b32_e64 v65, v65, 0, s[16:17]
	v_cndmask_b32_e64 v69, v69, 0, s[16:17]
	v_cndmask_b32_e64 v61, v61, 0, s[16:17]
	v_add_f32_e32 v42, v44, v42
	v_add_f32_e32 v43, v64, v43
	v_add_f32_e32 v44, v68, v62
	v_add_f32_e32 v58, v60, v58
	v_add_f32_e32 v42, v45, v42
	v_add_f32_e32 v43, v65, v43
	v_add_f32_e32 v44, v69, v44
	v_add_f32_e32 v45, v61, v58
	v_cndmask_b32_e64 v47, v47, 0, s[6:7]
	v_cndmask_b32_e64 v51, v51, 0, s[6:7]
	v_cndmask_b32_e64 v55, v55, 0, s[6:7]
	v_cndmask_b32_e64 v39, v39, 0, s[6:7]
	v_add_f32_e32 v42, v46, v42
	v_add_f32_e32 v43, v50, v43
	v_add_f32_e32 v44, v54, v44
	v_add_f32_e32 v38, v38, v45
	v_cndmask_b32_e64 v48, v48, 0, s[8:9]
	v_cndmask_b32_e64 v52, v52, 0, s[8:9]
	v_cndmask_b32_e64 v56, v56, 0, s[8:9]
	v_cndmask_b32_e64 v40, v40, 0, s[8:9]
	v_add_f32_e32 v42, v47, v42
	v_add_f32_e32 v43, v51, v43
	v_add_f32_e32 v44, v55, v44
	v_add_f32_e32 v38, v39, v38
	v_cndmask_b32_e64 v49, v49, 0, s[10:11]
	v_cndmask_b32_e64 v53, v53, 0, s[10:11]
	v_cndmask_b32_e64 v57, v57, 0, s[10:11]
	v_cndmask_b32_e64 v41, v41, 0, s[10:11]
	v_add_f32_e32 v39, v48, v42
	v_add_f32_e32 v42, v52, v43
	v_add_f32_e32 v43, v56, v44
	v_add_f32_e32 v38, v40, v38
	v_add_f32_e32 v39, v49, v39
	v_add_f32_e32 v40, v53, v42
	v_add_f32_e32 v42, v57, v43
	v_add_f32_e32 v38, v41, v38
	v_add_f32_e32 v35, v35, v39
	v_add_f32_e32 v32, v32, v40
	v_add_f32_e32 v34, v34, v42
	v_add_f32_e32 v33, v33, v38
	s_cbranch_scc1 .LBB0_378
	ds_bpermute_b32 v36, v167, v35
	ds_bpermute_b32 v37, v167, v32
	v_lshlrev_b32_e32 v156, 1, v168
	v_mov_b32_e32 v129, v134
	s_mov_b32 s20, 3
	s_waitcnt lgkmcnt(1)
	v_add_f32_e32 v35, v35, v36
	s_waitcnt lgkmcnt(0)
	v_add_f32_e32 v36, v32, v37
	ds_bpermute_b32 v37, v166, v35
	ds_bpermute_b32 v38, v166, v36
	v_mov_b32_e32 v32, 0
	v_mov_b32_e32 v43, v32
	v_mov_b32_e32 v44, v32
	s_waitcnt lgkmcnt(1)
	v_add_f32_e32 v35, v35, v37
	v_div_scale_f32 v37, s[6:7], v35, v35, 1.0
	s_waitcnt lgkmcnt(0)
	v_add_f32_e32 v36, v36, v38
	v_rcp_f32_e32 v38, v37
	v_div_scale_f32 v39, vcc, 1.0, v35, 1.0
	v_div_scale_f32 v40, s[6:7], v36, v36, 1.0
	v_fma_f32 v41, -v37, v38, 1.0
	v_fmac_f32_e32 v38, v41, v38
	v_mul_f32_e32 v41, v39, v38
	v_fma_f32 v42, -v37, v41, v39
	v_fmac_f32_e32 v41, v42, v38
	v_fma_f32 v37, -v37, v41, v39
	v_div_fmas_f32 v37, v37, v38, v41
	v_rcp_f32_e32 v38, v40
	v_div_fixup_f32 v37, v37, v35, 1.0
	v_cmp_lt_f32_e32 vcc, 0, v35
	v_mov_b32_e32 v42, v32
	v_fma_f32 v35, -v40, v38, 1.0
	v_fmac_f32_e32 v38, v35, v38
	ds_bpermute_b32 v35, v167, v34
	v_cndmask_b32_e32 v142, 0, v37, vcc
	v_div_scale_f32 v37, vcc, 1.0, v36, 1.0
	v_mul_f32_e32 v39, v37, v38
	s_waitcnt lgkmcnt(0)
	v_add_f32_e32 v34, v34, v35
	ds_bpermute_b32 v35, v166, v34
	v_fma_f32 v41, -v40, v39, v37
	v_fmac_f32_e32 v39, v41, v38
	v_fma_f32 v37, -v40, v39, v37
	v_div_fmas_f32 v37, v37, v38, v39
	s_waitcnt lgkmcnt(0)
	v_add_f32_e32 v34, v34, v35
	v_div_scale_f32 v35, s[6:7], v34, v34, 1.0
	v_rcp_f32_e32 v38, v35
	v_div_fixup_f32 v37, v37, v36, 1.0
	v_cmp_lt_f32_e32 vcc, 0, v36
	v_mov_b32_e32 v143, v142
	v_fma_f32 v36, -v35, v38, 1.0
	v_fmac_f32_e32 v38, v36, v38
	ds_bpermute_b32 v36, v167, v33
	v_cndmask_b32_e32 v144, 0, v37, vcc
	v_div_scale_f32 v37, vcc, 1.0, v34, 1.0
	v_mul_f32_e32 v39, v37, v38
	s_waitcnt lgkmcnt(0)
	v_add_f32_e32 v33, v33, v36
	ds_bpermute_b32 v36, v166, v33
	v_fma_f32 v40, -v35, v39, v37
	v_fmac_f32_e32 v39, v40, v38
	v_fma_f32 v35, -v35, v39, v37
	v_div_fmas_f32 v35, v35, v38, v39
	s_waitcnt lgkmcnt(0)
	v_add_f32_e32 v33, v33, v36
	v_div_scale_f32 v36, s[6:7], v33, v33, 1.0
	v_rcp_f32_e32 v37, v36
	v_div_fixup_f32 v35, v35, v34, 1.0
	v_cmp_lt_f32_e32 vcc, 0, v34
	s_add_u32 s6, s81, s1
	v_fma_f32 v34, -v36, v37, 1.0
	v_cndmask_b32_e32 v146, 0, v35, vcc
	v_fmac_f32_e32 v37, v34, v37
	v_div_scale_f32 v34, vcc, 1.0, v33, 1.0
	v_mul_f32_e32 v35, v34, v37
	v_fma_f32 v38, -v36, v35, v34
	v_fmac_f32_e32 v35, v38, v37
	v_fma_f32 v34, -v36, v35, v34
	v_div_fmas_f32 v34, v34, v37, v35
	v_div_fixup_f32 v34, v34, v33, 1.0
	v_cmp_lt_f32_e32 vcc, 0, v33
	s_addc_u32 s7, s82, 0
	v_lshlrev_b32_e32 v36, 4, v128
	v_cndmask_b32_e32 v148, 0, v34, vcc
	v_lshl_add_u64 v[34:35], v[138:139], 4, s[6:7]
	v_mov_b32_e32 v37, v133
	v_lshlrev_b32_e32 v33, 8, v128
	v_lshl_add_u64 v[150:151], v[34:35], 0, v[36:37]
	v_add3_u32 v155, s79, v33, v130
	v_mov_b32_e32 v145, v144
	v_mov_b32_e32 v147, v146
	v_mov_b32_e32 v149, v148
	v_mov_b32_e32 v33, v32
	v_mov_b32_e32 v34, v32
	v_mov_b32_e32 v35, v32
	v_mov_b32_e32 v36, v32
	v_mov_b32_e32 v37, v32
	v_mov_b32_e32 v38, v32
	v_mov_b32_e32 v39, v32
	v_mov_b32_e32 v40, v32
	v_mov_b32_e32 v41, v32
	v_mov_b32_e32 v45, v32
	v_mov_b32_e32 v46, v32
	v_mov_b32_e32 v47, v32
	v_mov_b32_e32 v48, v32
	v_mov_b32_e32 v49, v32
	v_mov_b32_e32 v50, v32
	v_mov_b32_e32 v51, v32
	v_mov_b32_e32 v52, v32
	v_mov_b32_e32 v53, v32
	v_mov_b32_e32 v54, v32
	v_mov_b32_e32 v55, v32
	v_mov_b32_e32 v56, v32
	v_mov_b32_e32 v57, v32
	v_mov_b32_e32 v58, v32
	v_mov_b32_e32 v59, v32
	v_mov_b32_e32 v60, v32
	v_mov_b32_e32 v61, v32
	v_mov_b32_e32 v62, v32
	v_mov_b32_e32 v63, v32
	v_mov_b32_e32 v64, v32
	v_mov_b32_e32 v65, v32
	v_mov_b32_e32 v66, v32
	v_mov_b32_e32 v67, v32
	v_mov_b32_e32 v68, v32
	v_mov_b32_e32 v69, v32
	v_mov_b32_e32 v70, v32
	v_mov_b32_e32 v71, v32
	v_mov_b32_e32 v72, v32
	v_mov_b32_e32 v73, v32
	v_mov_b32_e32 v74, v32
	v_mov_b32_e32 v75, v32
	v_mov_b32_e32 v76, v32
	v_mov_b32_e32 v77, v32
	v_mov_b32_e32 v78, v32
	v_mov_b32_e32 v79, v32
	v_mov_b32_e32 v80, v32
	v_mov_b32_e32 v81, v32
	v_mov_b32_e32 v82, v32
	v_mov_b32_e32 v83, v32
	v_mov_b32_e32 v84, v32
	v_mov_b32_e32 v85, v32
	v_mov_b32_e32 v86, v32
	v_mov_b32_e32 v87, v32
	v_mov_b32_e32 v88, v32
	v_mov_b32_e32 v89, v32
	v_mov_b32_e32 v90, v32
	v_mov_b32_e32 v91, v32
	v_mov_b32_e32 v92, v32
	v_mov_b32_e32 v93, v32
	v_mov_b32_e32 v94, v32
	v_mov_b32_e32 v95, v32
	s_branch .LBB0_381

.LBB0_381:
	s_add_i32 s6, s20, -3
	s_ashr_i32 s7, s6, 31
	s_lshl_b64 s[8:9], s[6:7], 10
	v_lshl_add_u64 v[96:97], v[140:141], 0, s[8:9]
	global_load_dwordx4 v[112:115], v[96:97], off
	s_add_i32 s8, s20, -1
	s_ashr_i32 s9, s8, 31
	s_lshl_b64 s[10:11], s[8:9], 10
	v_lshl_add_u64 v[98:99], v[140:141], 0, s[10:11]
	global_load_dwordx4 v[108:111], v[98:99], off
	global_load_dwordx4 v[116:119], v[96:97], off offset:1024
	global_load_dwordx4 v[104:107], v[98:99], off offset:1024
	v_or_b32_e32 v160, 31, v153
	v_or_b32_e32 v176, 47, v153
	v_add_u32_e32 v120, 64, v154
	v_sub_u32_e32 v124, v134, v160
	v_sub_u32_e32 v125, v134, v176
	v_cvt_f32_i32_e32 v208, v120
	v_cvt_f32_i32_e32 v209, v124
	v_cvt_f32_i32_e32 v210, v125
	v_or_b32_e32 v159, 0x5f, v153
	v_or_b32_e32 v161, 0x6f, v153
	v_or_b32_e32 v177, 0x7f, v153
	v_or_b32_e32 v186, 63, v153
	v_sub_u32_e32 v175, v134, v159
	v_sub_u32_e32 v174, v134, v186
	v_sub_u32_e32 v178, v134, v161
	v_sub_u32_e32 v179, v134, v177
	v_cvt_f32_i32_e32 v212, v175
	v_cvt_f32_i32_e32 v180, v154
	v_cvt_f32_i32_e32 v211, v174
	v_cvt_f32_i32_e32 v213, v178
	v_cvt_f32_i32_e32 v214, v179
	s_mov_b32 s7, s49
	s_lshl_b64 s[6:7], s[6:7], 10
	s_add_i32 s48, s20, -2
	v_lshl_add_u64 v[96:97], v[150:151], 0, s[6:7]
	s_lshl_b64 s[6:7], s[48:49], 10
	s_mov_b32 s9, s49
	v_lshl_add_u64 v[100:101], v[150:151], 0, s[6:7]
	v_add_u32_e32 v157, 0x4f, v153
	v_add_u32_e32 v158, 0x8f, v153
	s_lshl_b64 s[6:7], s[8:9], 10
	v_cmp_gt_i32_e64 s[12:13], v159, v129
	v_cmp_gt_i32_e64 s[14:15], v160, v134
	s_mov_b32 s21, s49
	v_lshl_add_u64 v[174:175], v[150:151], 0, s[6:7]
	v_cmp_gt_i32_e64 s[16:17], v161, v129
	v_cmp_gt_i32_e64 s[18:19], v176, v134
	v_cmp_gt_i32_e32 vcc, v177, v129
	v_cmp_gt_i32_e64 s[6:7], v186, v134
	v_cmp_gt_i32_e64 s[8:9], v158, v129
	v_cmp_gt_i32_e64 s[10:11], v157, v134
	s_lshl_b64 s[24:25], s[20:21], 10
	global_load_dwordx4 v[96:99], v[96:97], off
	s_waitcnt vmcnt(3)
	v_mfma_f32_16x16x32_bf16 v[124:127], v[108:111], v[0:3], v[244:247]
	global_load_dwordx4 v[100:103], v[100:101], off
	v_mfma_f32_16x16x32_bf16 v[120:123], v[112:115], v[0:3], v[244:247]
	s_waitcnt vmcnt(3)
	v_mfma_f32_16x16x32_bf16 v[120:123], v[116:119], v[4:7], v[120:123]
	s_waitcnt vmcnt(2)
	v_mfma_f32_16x16x32_bf16 v[124:127], v[104:107], v[4:7], v[124:127]
	s_nop 5
	s_nop 0
	v_fma_f32 v120, -v170, v209, v120
	v_fma_f32 v124, -v170, v212, v124
	v_fma_f32 v123, -v170, v208, v123
	v_fma_f32 v127, -v170, v180, v127
	v_fma_f32 v121, -v170, v210, v121
	v_fma_f32 v122, -v170, v211, v122
	v_fma_f32 v125, -v170, v213, v125
	v_fma_f32 v126, -v170, v214, v126
	v_exp_f32_e32 v120, v120
	v_exp_f32_e32 v124, v124
	v_exp_f32_e32 v123, v123
	v_exp_f32_e32 v127, v127
	v_exp_f32_e32 v121, v121
	v_exp_f32_e32 v122, v122
	v_exp_f32_e32 v125, v125
	v_exp_f32_e32 v126, v126
	v_cndmask_b32_e64 v179, v124, 0, s[12:13]
	v_cndmask_b32_e64 v178, v120, 0, s[14:15]
	v_cndmask_b32_e64 v185, v125, 0, s[16:17]
	v_cndmask_b32_e64 v184, v121, 0, s[18:19]
	v_cndmask_b32_e64 v187, v126, 0, vcc
	v_cndmask_b32_e64 v186, v122, 0, s[6:7]
	v_cndmask_b32_e64 v189, v127, 0, s[8:9]
	v_cndmask_b32_e64 v188, v123, 0, s[10:11]
	v_mul_f32_e32 v120, v142, v178
	v_mul_f32_e32 v121, v143, v179
	v_mul_f32_e32 v122, v142, v184
	v_mul_f32_e32 v123, v143, v185
	v_mul_f32_e32 v124, v142, v186
	v_mul_f32_e32 v125, v143, v187
	v_mul_f32_e32 v126, v142, v188
	v_mul_f32_e32 v127, v143, v189
	v_cvt_pk_bf16_f32 v158, v120, v122
	v_cvt_pk_bf16_f32 v160, v121, v123
	v_lshl_add_u64 v[120:121], v[150:151], 0, s[24:25]
	v_cvt_pk_bf16_f32 v159, v124, v126
	v_cvt_pk_bf16_f32 v161, v125, v127
	global_load_dwordx4 v[124:127], v[174:175], off
	s_waitcnt vmcnt(2)
	v_mfma_f32_16x16x32_bf16 v[92:95], v[96:99], v[158:161], v[92:95]
	global_load_dwordx4 v[120:123], v[120:121], off
	s_waitcnt vmcnt(2)
	v_mfma_f32_16x16x32_bf16 v[88:91], v[100:103], v[158:161], v[88:91]
	v_mfma_f32_16x16x32_bf16 v[174:177], v[108:111], v[8:11], v[244:247]
	s_waitcnt vmcnt(1)
	v_mfma_f32_16x16x32_bf16 v[84:87], v[124:127], v[158:161], v[84:87]
	s_waitcnt vmcnt(0)
	v_mfma_f32_16x16x32_bf16 v[80:83], v[120:123], v[158:161], v[80:83]
	v_mfma_f32_16x16x32_bf16 v[158:161], v[112:115], v[8:11], v[244:247]
	v_mfma_f32_16x16x32_bf16 v[158:161], v[116:119], v[12:15], v[158:161]
	s_nop 7
	v_mov_b32_e32 v157, v158
	v_fma_f32 v158, -v171, v210, v159
	v_exp_f32_e32 v192, v158
	v_fma_f32 v158, -v171, v211, v160
	v_exp_f32_e32 v194, v158
	v_fma_f32 v158, -v171, v208, v161
	v_exp_f32_e32 v196, v158
	v_mfma_f32_16x16x32_bf16 v[158:161], v[104:107], v[12:15], v[174:177]
	v_fma_f32 v157, -v171, v209, v157
	v_exp_f32_e32 v157, v157
	v_cndmask_b32_e64 v194, v194, 0, s[6:7]
	v_cndmask_b32_e64 v192, v192, 0, s[18:19]
	v_cndmask_b32_e64 v196, v196, 0, s[10:11]
	s_nop 2
	v_fma_f32 v158, -v171, v212, v158
	v_exp_f32_e32 v158, v158
	v_cndmask_b32_e64 v190, v157, 0, s[14:15]
	v_cndmask_b32_e64 v191, v158, 0, s[12:13]
	v_fma_f32 v157, -v171, v214, v160
	v_fma_f32 v159, -v171, v213, v159
	v_exp_f32_e32 v157, v157
	v_fma_f32 v158, -v171, v180, v161
	v_exp_f32_e32 v159, v159
	v_exp_f32_e32 v158, v158
	v_cndmask_b32_e64 v195, v157, 0, vcc
	v_mul_f32_e32 v160, v144, v194
	v_mul_f32_e32 v161, v145, v195
	v_cndmask_b32_e64 v193, v159, 0, s[16:17]
	v_cndmask_b32_e64 v197, v158, 0, s[8:9]
	v_mul_f32_e32 v174, v144, v190
	v_mul_f32_e32 v175, v145, v191
	v_mul_f32_e32 v176, v144, v192
	v_mul_f32_e32 v177, v145, v193
	v_mul_f32_e32 v198, v144, v196
	v_mul_f32_e32 v199, v145, v197
	v_cvt_pk_bf16_f32 v158, v174, v176
	s_nop 0
	v_cvt_pk_bf16_f32 v159, v160, v198
	v_cvt_pk_bf16_f32 v160, v175, v177
	v_cvt_pk_bf16_f32 v161, v161, v199
	v_mfma_f32_16x16x32_bf16 v[174:177], v[108:111], v[16:19], v[244:247]
	s_nop 0
	v_mfma_f32_16x16x32_bf16 v[76:79], v[96:99], v[158:161], v[76:79]
	v_mfma_f32_16x16x32_bf16 v[72:75], v[100:103], v[158:161], v[72:75]
	v_mfma_f32_16x16x32_bf16 v[68:71], v[124:127], v[158:161], v[68:71]
	v_mfma_f32_16x16x32_bf16 v[64:67], v[120:123], v[158:161], v[64:67]
	v_mfma_f32_16x16x32_bf16 v[158:161], v[112:115], v[16:19], v[244:247]
	v_mfma_f32_16x16x32_bf16 v[158:161], v[116:119], v[20:23], v[158:161]
	v_mfma_f32_16x16x32_bf16 v[108:111], v[108:111], v[24:27], v[244:247]
	v_mfma_f32_16x16x32_bf16 v[112:115], v[112:115], v[24:27], v[244:247]
	s_nop 5
	v_mov_b32_e32 v157, v158
	v_fma_f32 v158, -v172, v210, v159
	v_exp_f32_e32 v198, v158
	v_fma_f32 v158, -v172, v211, v160
	v_exp_f32_e32 v202, v158
	v_fma_f32 v158, -v172, v208, v161
	v_exp_f32_e32 v204, v158
	v_mfma_f32_16x16x32_bf16 v[158:161], v[104:107], v[20:23], v[174:177]
	v_fma_f32 v157, -v172, v209, v157
	v_exp_f32_e32 v157, v157
	v_cndmask_b32_e64 v202, v202, 0, s[6:7]
	v_mfma_f32_16x16x32_bf16 v[104:107], v[104:107], v[28:31], v[108:111]
	v_cndmask_b32_e64 v198, v198, 0, s[18:19]
	s_nop 2
	v_fma_f32 v158, -v172, v212, v158
	v_mfma_f32_16x16x32_bf16 v[112:115], v[116:119], v[28:31], v[112:115]
	v_exp_f32_e32 v158, v158
	v_cndmask_b32_e64 v174, v157, 0, s[14:15]
	v_fma_f32 v104, -v173, v212, v104
	s_nop 2
	v_fma_f32 v157, -v172, v214, v160
	s_nop 0
	v_fma_f32 v113, -v173, v210, v113
	v_exp_f32_e32 v104, v104
	v_fma_f32 v105, -v173, v213, v105
	v_exp_f32_e32 v157, v157
	v_exp_f32_e32 v116, v113
	v_exp_f32_e32 v105, v105
	v_cndmask_b32_e64 v175, v158, 0, s[12:13]
	v_fma_f32 v113, -v173, v211, v114
	v_fma_f32 v159, -v172, v213, v159
	v_fma_f32 v158, -v172, v180, v161
	v_exp_f32_e32 v118, v113
	v_exp_f32_e32 v159, v159
	v_exp_f32_e32 v158, v158
	v_fma_f32 v113, -v173, v208, v115
	v_cndmask_b32_e64 v109, v104, 0, s[12:13]
	v_cndmask_b32_e64 v203, v157, 0, vcc
	v_fma_f32 v112, -v173, v209, v112
	v_exp_f32_e32 v157, v113
	v_cndmask_b32_e64 v113, v105, 0, s[16:17]
	v_fma_f32 v104, -v173, v214, v106
	v_exp_f32_e32 v112, v112
	v_exp_f32_e32 v104, v104
	v_fma_f32 v105, -v173, v180, v107
	v_exp_f32_e32 v105, v105
	v_cndmask_b32_e64 v199, v159, 0, s[16:17]
	v_mul_f32_e32 v160, v146, v202
	v_mul_f32_e32 v161, v147, v203
	v_cndmask_b32_e64 v205, v158, 0, s[8:9]
	v_cndmask_b32_e64 v204, v204, 0, s[10:11]
	v_mul_f32_e32 v176, v146, v174
	v_mul_f32_e32 v177, v147, v175
	v_mul_f32_e32 v200, v146, v198
	v_mul_f32_e32 v201, v147, v199
	v_mul_f32_e32 v206, v146, v204
	v_mul_f32_e32 v207, v147, v205
	v_cvt_pk_bf16_f32 v158, v176, v200
	v_cndmask_b32_e64 v108, v112, 0, s[14:15]
	v_cvt_pk_bf16_f32 v159, v160, v206
	v_cvt_pk_bf16_f32 v160, v177, v201
	v_cvt_pk_bf16_f32 v161, v161, v207
	v_fma_f32 v176, v142, v178, 0
	v_fma_f32 v177, v143, v179, 0
	v_mfma_f32_16x16x32_bf16 v[60:63], v[96:99], v[158:161], v[60:63]
	v_cndmask_b32_e64 v112, v116, 0, s[18:19]
	v_cndmask_b32_e64 v117, v104, 0, vcc
	v_cndmask_b32_e64 v116, v118, 0, s[6:7]
	v_mfma_f32_16x16x32_bf16 v[56:59], v[100:103], v[158:161], v[56:59]
	v_fma_f32 v176, v144, v190, v176
	v_fma_f32 v177, v145, v191, v177
	v_mul_f32_e32 v106, v148, v116
	v_mul_f32_e32 v107, v149, v117
	v_cndmask_b32_e64 v119, v105, 0, s[8:9]
	v_mfma_f32_16x16x32_bf16 v[52:55], v[124:127], v[158:161], v[52:55]
	v_cndmask_b32_e64 v118, v157, 0, s[10:11]
	v_fma_f32 v178, v142, v184, 0
	v_fma_f32 v179, v143, v185, 0
	v_mul_f32_e32 v110, v148, v108
	v_mul_f32_e32 v111, v149, v109
	v_mfma_f32_16x16x32_bf16 v[48:51], v[120:123], v[158:161], v[48:51]
	v_fma_f32 v160, v142, v188, 0
	v_fma_f32 v161, v143, v189, 0
	v_fma_f32 v158, v142, v186, 0
	v_fma_f32 v159, v143, v187, 0
	v_fma_f32 v160, v144, v196, v160
	v_fma_f32 v161, v145, v197, v161
	v_mul_f32_e32 v114, v148, v112
	v_mul_f32_e32 v115, v149, v113
	v_mul_f32_e32 v184, v148, v118
	v_mul_f32_e32 v185, v149, v119
	v_cvt_pk_bf16_f32 v104, v110, v114
	v_fma_f32 v178, v144, v192, v178
	v_fma_f32 v179, v145, v193, v179
	v_cvt_pk_bf16_f32 v105, v106, v184
	v_cvt_pk_bf16_f32 v106, v111, v115
	v_cvt_pk_bf16_f32 v107, v107, v185
	v_fma_f32 v158, v144, v194, v158
	v_fma_f32 v159, v145, v195, v159
	v_mfma_f32_16x16x32_bf16 v[44:47], v[96:99], v[104:107], v[44:47]
	v_fma_f32 v96, v146, v174, v176
	v_fma_f32 v97, v147, v175, v177
	v_fma_f32 v98, v146, v198, v178
	v_fma_f32 v99, v147, v199, v179
	v_fma_f32 v110, v146, v202, v158
	v_fma_f32 v111, v147, v203, v159
	v_mfma_f32_16x16x32_bf16 v[40:43], v[100:103], v[104:107], v[40:43]
	v_fma_f32 v100, v146, v204, v160
	v_fma_f32 v101, v147, v205, v161
	v_fma_f32 v102, v148, v108, v96
	v_fma_f32 v103, v149, v109, v97
	v_fma_f32 v96, v148, v118, v100
	v_fma_f32 v97, v149, v119, v101
	ds_read_b64 v[100:101], v155
	v_fma_f32 v98, v148, v112, v98
	v_fma_f32 v99, v149, v113, v99
	v_fma_f32 v108, v148, v116, v110
	v_fma_f32 v109, v149, v117, v111
	v_add_f32_e32 v98, v102, v98
	v_add_f32_e32 v99, v103, v99
	v_add_f32_e32 v102, v108, v96
	v_add_f32_e32 v103, v109, v97
	v_mfma_f32_16x16x32_bf16 v[36:39], v[124:127], v[104:107], v[36:39]
	v_add_f32_e64 v98, v98, v102
	v_add_f32_e64 v99, v99, v103
	v_cmp_gt_i32_e32 vcc, 63, v156
	s_waitcnt lgkmcnt(0)
	v_add_f32_e32 v98, v98, v100
	v_add_f32_e32 v99, v99, v101
	v_mfma_f32_16x16x32_bf16 v[32:35], v[120:123], v[104:107], v[32:35]
	ds_write_b64 v155, v[98:99]
	s_waitcnt lgkmcnt(0)
	s_and_saveexec_b64 s[6:7], vcc
	s_cbranch_execz .LBB0_383
	ds_read_b32 v98, v155 offset:4
	s_waitcnt lgkmcnt(0)
	v_add_f32_e32 v96, v96, v98
	ds_write_b32 v155, v96 offset:4

.LBB0_398:
	s_lshr_b32 s8, s26, 1
	s_sub_i32 s9, s8, 32
	s_cmp_lt_u32 s26, 64
	s_cselect_b64 vcc, -1, 0
	s_and_b64 s[6:7], vcc, exec
	s_cselect_b32 s6, s8, s9
	v_cndmask_b32_e32 v96, v141, v140, vcc
	s_lshl_b32 s6, 1, s6
	v_and_b32_e32 v96, s6, v96
	v_cmp_ne_u32_e64 s[8:9], 0, v96
	s_mov_b64 vcc, s[8:9]
	s_cbranch_vccz .LBB0_397
	v_add_u32_e32 v152, s1, v130
	s_waitcnt vmcnt(0)
	ds_read_b128 v[124:127], v252 offset:4096
	ds_read_b128 v[120:123], v252 offset:5120
	ds_read_b128 v[116:119], v252 offset:6144
	ds_read_b128 v[112:115], v252 offset:7168
	ds_read_b128 v[108:111], v252 offset:8192
	ds_read_b128 v[104:107], v252 offset:9216
	ds_read_b128 v[100:103], v252 offset:10240
	ds_read_b128 v[96:99], v252 offset:11264
	s_add_i32 s10, s26, 1
	s_lshr_b32 s11, s26, 1
	s_add_i32 s11, s11, 1
	s_lshr_b64 s[12:13], s[98:99], s11
	s_ff1_i32_b64 s14, s[12:13]
	s_cmp_lt_i32 s14, 0
	s_cselect_b32 s14, 0, s14
	s_add_i32 s14, s14, s11
	s_lshl_b32 s14, s14, 1
	s_bitcmp1_b32 s26, 0
	s_cselect_b32 s10, s14, s10
	s_sub_i32 s10, s10, s26
	s_lshl_b32 s10, s10, 12
	s_add_i32 s10, s10, 0xfffff400
	v_add_co_u32_e32 v248, vcc, s10, v138
	s_nop 1
	v_addc_co_u32_e32 v249, vcc, 0, v139, vcc
	v_add_co_u32_e32 v250, vcc, 0xff000000, v248
	s_nop 1
	v_addc_co_u32_e32 v251, vcc, -1, v249, vcc
	v_add_u32_e32 v180, s80, v131
	v_add_u32_e32 v200, -1, v180
	v_add_u32_e32 v204, 2, v152
	v_add_u32_e32 v205, -2, v180
	v_add_u32_e32 v206, 3, v152
	v_cvt_f32_i32_e32 v223, v200
	v_cmp_le_i32_e64 s[12:13], v204, v134
	v_cvt_f32_i32_e32 v224, v205
	v_cmp_le_i32_e64 s[14:15], v206, v134
	v_cmp_le_i32_e32 vcc, v152, v134
	v_cvt_f32_i32_e32 v222, v180
	v_cmp_lt_i32_e64 s[6:7], v152, v134
	v_add_u32_e32 v208, -3, v180
	v_add_u32_e32 v209, 4, v152
	v_add_u32_e32 v210, -4, v180
	v_add_u32_e32 v211, 5, v152
	v_add_u32_e32 v212, -5, v180
	v_add_u32_e32 v213, 6, v152
	v_add_u32_e32 v214, -6, v180
	v_add_u32_e32 v152, 7, v152
	v_add_u32_e32 v180, -7, v180
	v_cvt_f32_i32_e32 v227, v212
	v_cvt_f32_i32_e32 v228, v214
	v_cmp_le_i32_e64 s[24:25], v152, v134
	v_cvt_f32_i32_e32 v152, v180
	v_cmp_le_i32_e64 s[16:17], v209, v134
	v_cmp_le_i32_e64 s[20:21], v211, v134
	v_cmp_le_i32_e64 s[22:23], v213, v134
	s_and_b64 s[18:19], s[8:9], vcc
	s_and_b64 s[10:11], s[8:9], s[6:7]
	s_and_b64 s[12:13], s[8:9], s[12:13]
	s_and_b64 s[14:15], s[8:9], s[14:15]
	s_and_b64 s[16:17], s[8:9], s[16:17]
	s_and_b64 vcc, s[8:9], s[20:21]
	s_and_b64 s[6:7], s[8:9], s[22:23]
	s_and_b64 s[8:9], s[24:25], s[8:9]
	v_cvt_f32_i32_e32 v225, v208
	v_cvt_f32_i32_e32 v226, v210
	s_waitcnt lgkmcnt(0)
	s_add_i32 m0, s79, 0x1000
	s_nop 0
	global_load_lds_dwordx4 v[250:251], off
	global_load_lds_dwordx4 v[250:251], off offset:1024
	global_load_lds_dwordx4 v[250:251], off offset:2048
	global_load_lds_dwordx4 v[250:251], off offset:3072
	s_add_i32 m0, s79, 0x2000
	s_nop 0
	global_load_lds_dwordx4 v[248:249], off
	global_load_lds_dwordx4 v[248:249], off offset:1024
	global_load_lds_dwordx4 v[248:249], off offset:2048
	global_load_lds_dwordx4 v[248:249], off offset:3072
	v_mfma_f32_16x16x32_bf16 v[196:199], v[124:127], v[0:3], v[244:247]
	v_mfma_f32_16x16x32_bf16 v[200:203], v[116:119], v[0:3], v[244:247]
	v_mfma_f32_16x16x32_bf16 v[204:207], v[124:127], v[8:11], v[244:247]
	v_mfma_f32_16x16x32_bf16 v[196:199], v[120:123], v[4:7], v[196:199]
	v_mfma_f32_16x16x32_bf16 v[200:203], v[112:115], v[4:7], v[200:203]
	v_mfma_f32_16x16x32_bf16 v[204:207], v[120:123], v[12:15], v[204:207]
	s_nop 4
	s_nop 0
	v_mov_b32_e32 v180, v196
	v_mov_b32_e32 v196, v197
	v_mov_b32_e32 v197, v198
	v_mov_b32_e32 v198, v199
	v_mov_b32_e32 v199, v200
	v_mov_b32_e32 v200, v201
	v_mov_b32_e32 v201, v202
	v_mov_b32_e32 v202, v203
	v_fma_f32 v200, -v170, v227, v200
	v_fma_f32 v201, -v170, v228, v201
	v_fma_f32 v202, -v170, v152, v202
	v_fma_f32 v203, -v171, v222, v204
	v_exp_f32_e32 v200, v200
	v_exp_f32_e32 v201, v201
	v_exp_f32_e32 v202, v202
	v_exp_f32_e32 v203, v203
	v_fma_f32 v204, -v171, v223, v205
	v_exp_f32_e32 v208, v204
	v_cndmask_b32_e32 v217, 0, v200, vcc
	v_cndmask_b32_e64 v219, 0, v201, s[6:7]
	v_cndmask_b32_e64 v221, 0, v202, s[8:9]
	v_cndmask_b32_e64 v204, 0, v203, s[18:19]
	v_mfma_f32_16x16x32_bf16 v[200:203], v[116:119], v[8:11], v[244:247]
	v_fma_f32 v180, -v170, v222, v180
	v_exp_f32_e32 v180, v180
	v_mfma_f32_16x16x32_bf16 v[200:203], v[112:115], v[12:15], v[200:203]
	v_fma_f32 v196, -v170, v223, v196
	v_cndmask_b32_e64 v205, 0, v180, s[18:19]
	v_fma_f32 v180, -v171, v224, v206
	v_exp_f32_e32 v180, v180
	v_fma_f32 v197, -v170, v224, v197
	s_nop 2
	v_fma_f32 v200, -v171, v226, v200
	v_exp_f32_e32 v200, v200
	v_cndmask_b32_e64 v210, 0, v180, s[12:13]
	v_mov_b32_e32 v180, v201
	v_cndmask_b32_e64 v214, 0, v200, s[16:17]
	v_fma_f32 v200, -v171, v228, v202
	v_fma_f32 v201, -v171, v152, v203
	v_fma_f32 v198, -v170, v225, v198
	v_exp_f32_e32 v196, v196
	v_exp_f32_e32 v200, v200
	v_exp_f32_e32 v201, v201
	v_fma_f32 v199, -v170, v226, v199
	v_exp_f32_e32 v197, v197
	v_exp_f32_e32 v198, v198
	v_fma_f32 v206, -v171, v225, v207
	v_exp_f32_e32 v199, v199
	v_exp_f32_e32 v206, v206
	v_fma_f32 v180, -v171, v227, v180
	v_exp_f32_e32 v180, v180
	v_cndmask_b32_e64 v209, 0, v196, s[10:11]
	v_cndmask_b32_e64 v208, 0, v208, s[10:11]
	v_cndmask_b32_e64 v218, 0, v200, s[6:7]
	v_cndmask_b32_e64 v220, 0, v201, s[8:9]
	v_add_f32_e32 v200, 0, v204
	v_add_f32_e32 v201, 0, v205
	v_cndmask_b32_e64 v211, 0, v197, s[12:13]
	v_cndmask_b32_e64 v213, 0, v198, s[14:15]
	v_cvt_pk_bf16_f32 v196, v205, v209
	v_cvt_pk_bf16_f32 v197, v211, v213
	v_add_f32_e32 v200, v208, v200
	v_add_f32_e32 v201, v209, v201
	v_cndmask_b32_e64 v215, 0, v199, s[16:17]
	v_cvt_pk_bf16_f32 v198, v215, v217
	v_cvt_pk_bf16_f32 v199, v219, v221
	v_cndmask_b32_e64 v212, 0, v206, s[14:15]
	s_nop 0
	v_mfma_f32_16x16x32_bf16 v[92:95], v[108:111], v[196:199], v[92:95]
	v_add_f32_e64 v200, v210, v200
	v_add_f32_e64 v201, v211, v201
	v_cndmask_b32_e32 v216, 0, v180, vcc
	v_mfma_f32_16x16x32_bf16 v[88:91], v[104:107], v[196:199], v[88:91]
	v_mfma_f32_16x16x32_bf16 v[84:87], v[100:103], v[196:199], v[84:87]
	v_mfma_f32_16x16x32_bf16 v[80:83], v[96:99], v[196:199], v[80:83]
	v_cvt_pk_bf16_f32 v196, v204, v208
	v_cvt_pk_bf16_f32 v197, v210, v212
	v_cvt_pk_bf16_f32 v198, v214, v216
	v_cvt_pk_bf16_f32 v199, v218, v220
	s_nop 0
	s_nop 0
	v_mfma_f32_16x16x32_bf16 v[76:79], v[108:111], v[196:199], v[76:79]
	v_mfma_f32_16x16x32_bf16 v[72:75], v[104:107], v[196:199], v[72:75]
	v_mfma_f32_16x16x32_bf16 v[68:71], v[100:103], v[196:199], v[68:71]
	v_mfma_f32_16x16x32_bf16 v[64:67], v[96:99], v[196:199], v[64:67]
	v_add_f32_e64 v196, v212, v200
	v_add_f32_e64 v197, v213, v201
	v_add_f32_e32 v196, v214, v196
	v_add_f32_e32 v197, v215, v197
	s_nop 0
	v_add_f32_e32 v200, v216, v196
	v_add_f32_e32 v201, v217, v197
	v_mfma_f32_16x16x32_bf16 v[196:199], v[124:127], v[16:19], v[244:247]
	v_add_f32_e64 v200, v218, v200
	v_add_f32_e64 v201, v219, v201
	v_add_f32_e32 v200, v220, v200
	v_add_f32_e32 v201, v221, v201
	v_mfma_f32_16x16x32_bf16 v[196:199], v[120:123], v[20:23], v[196:199]
	v_add_f32_e64 v146, v146, v200
	v_add_f32_e64 v147, v147, v201
	v_mfma_f32_16x16x32_bf16 v[200:203], v[116:119], v[16:19], v[244:247]
	v_mfma_f32_16x16x32_bf16 v[124:127], v[124:127], v[24:27], v[244:247]
	s_nop 3
	v_mov_b32_e32 v180, v196
	v_fma_f32 v196, -v172, v223, v197
	v_exp_f32_e32 v204, v196
	v_mfma_f32_16x16x32_bf16 v[116:119], v[116:119], v[24:27], v[244:247]
	v_fma_f32 v196, -v172, v224, v198
	v_exp_f32_e32 v205, v196
	v_fma_f32 v196, -v172, v225, v199
	v_exp_f32_e32 v206, v196
	v_mfma_f32_16x16x32_bf16 v[196:199], v[112:115], v[20:23], v[200:203]
	v_fma_f32 v180, -v172, v222, v180
	v_exp_f32_e32 v180, v180
	v_cndmask_b32_e64 v205, 0, v205, s[12:13]
	v_mfma_f32_16x16x32_bf16 v[120:123], v[120:123], v[28:31], v[124:127]
	v_cndmask_b32_e64 v203, 0, v204, s[10:11]
	s_nop 2
	v_mfma_f32_16x16x32_bf16 v[112:115], v[112:115], v[28:31], v[116:119]
	s_nop 2
	v_fma_f32 v120, -v173, v222, v120
	v_exp_f32_e32 v120, v120
	s_nop 2
	v_fma_f32 v112, -v173, v226, v112
	v_exp_f32_e32 v112, v112
	v_cndmask_b32_e64 v200, 0, v120, s[18:19]
	v_mov_b32_e32 v120, v121
	v_mov_b32_e32 v121, v122
	v_cndmask_b32_e64 v208, 0, v112, s[16:17]
	v_mov_b32_e32 v112, v113
	v_mov_b32_e32 v113, v114
	v_fma_f32 v196, -v172, v226, v196
	v_fma_f32 v197, -v172, v227, v197
	v_fma_f32 v198, -v172, v228, v198
	v_fma_f32 v199, -v172, v152, v199
	v_fma_f32 v120, -v173, v223, v120
	v_fma_f32 v121, -v173, v224, v121
	v_fma_f32 v122, -v173, v225, v123
	v_fma_f32 v112, -v173, v227, v112
	v_fma_f32 v113, -v173, v228, v113
	v_fma_f32 v114, -v173, v152, v115
	v_exp_f32_e32 v196, v196
	v_exp_f32_e32 v197, v197
	v_exp_f32_e32 v198, v198
	v_exp_f32_e32 v199, v199
	v_exp_f32_e32 v120, v120
	v_exp_f32_e32 v121, v121
	v_exp_f32_e32 v122, v122
	v_exp_f32_e32 v112, v112
	v_exp_f32_e32 v113, v113
	v_exp_f32_e32 v114, v114
	v_cndmask_b32_e64 v201, 0, v180, s[18:19]
	v_cndmask_b32_e64 v207, 0, v206, s[14:15]
	v_cndmask_b32_e64 v209, 0, v196, s[16:17]
	v_cndmask_b32_e32 v211, 0, v197, vcc
	v_cndmask_b32_e64 v213, 0, v198, s[6:7]
	v_cndmask_b32_e64 v215, 0, v199, s[8:9]
	v_cvt_pk_bf16_f32 v196, v201, v203
	v_cvt_pk_bf16_f32 v197, v205, v207
	v_cvt_pk_bf16_f32 v198, v209, v211
	v_cvt_pk_bf16_f32 v199, v213, v215
	v_cndmask_b32_e64 v202, 0, v120, s[10:11]
	v_cndmask_b32_e64 v204, 0, v121, s[12:13]
	v_cndmask_b32_e64 v206, 0, v122, s[14:15]
	v_mfma_f32_16x16x32_bf16 v[60:63], v[108:111], v[196:199], v[60:63]
	v_cndmask_b32_e32 v210, 0, v112, vcc
	v_cndmask_b32_e64 v212, 0, v113, s[6:7]
	v_cndmask_b32_e64 v214, 0, v114, s[8:9]
	v_cvt_pk_bf16_f32 v112, v200, v202
	v_cvt_pk_bf16_f32 v113, v204, v206
	v_cvt_pk_bf16_f32 v114, v208, v210
	v_cvt_pk_bf16_f32 v115, v212, v214
	v_mfma_f32_16x16x32_bf16 v[56:59], v[104:107], v[196:199], v[56:59]
	s_nop 0
	v_mfma_f32_16x16x32_bf16 v[44:47], v[108:111], v[112:115], v[44:47]
	v_add_f32_e64 v108, v200, 0
	v_add_f32_e64 v109, v201, 0
	v_add_f32_e32 v108, v202, v108
	v_add_f32_e32 v109, v203, v109
	v_mfma_f32_16x16x32_bf16 v[40:43], v[104:107], v[112:115], v[40:43]
	v_add_f32_e64 v108, v204, v108
	v_add_f32_e64 v109, v205, v109
	v_add_f32_e32 v104, v206, v108
	v_add_f32_e32 v105, v207, v109
	v_mfma_f32_16x16x32_bf16 v[52:55], v[100:103], v[196:199], v[52:55]
	v_add_f32_e64 v104, v208, v104
	v_add_f32_e64 v105, v209, v105
	v_add_f32_e32 v104, v210, v104
	v_add_f32_e32 v105, v211, v105
	v_mfma_f32_16x16x32_bf16 v[48:51], v[96:99], v[196:199], v[48:51]
	v_mfma_f32_16x16x32_bf16 v[36:39], v[100:103], v[112:115], v[36:39]
	v_add_f32_e64 v100, v212, v104
	v_add_f32_e64 v101, v213, v105
	v_add_f32_e32 v100, v214, v100
	v_add_f32_e32 v101, v215, v101
	v_mfma_f32_16x16x32_bf16 v[32:35], v[96:99], v[112:115], v[32:35]
	v_add_f32_e64 v142, v142, v100
	v_add_f32_e64 v143, v143, v101
	s_branch .LBB0_397

.LBB0_402:
	v_add_u32_e32 v128, -7, v211
	v_add_co_u32_e32 v250, vcc, 0xff000400, v144
	s_nop 1
	v_addc_co_u32_e32 v251, vcc, -1, v145, vcc
	v_add_co_u32_e32 v248, vcc, 0x400, v144
	s_nop 1
	v_addc_co_u32_e32 v249, vcc, 0, v145, vcc
	s_waitcnt vmcnt(0)
	ds_read_b128 v[120:123], v252 offset:4096
	ds_read_b128 v[124:127], v252 offset:5120
	ds_read_b128 v[116:119], v252 offset:6144
	ds_read_b128 v[112:115], v252 offset:7168
	ds_read_b128 v[96:99], v252 offset:8192
	ds_read_b128 v[100:103], v252 offset:9216
	ds_read_b128 v[104:107], v252 offset:10240
	ds_read_b128 v[108:111], v252 offset:11264
	v_add_u32_e32 v129, 7, v210
	v_cmp_le_i32_e32 vcc, v128, v134
	v_cmp_gt_i32_e64 s[6:7], s91, v129
	s_and_b64 s[12:13], vcc, s[6:7]
	v_cmp_lt_i32_e32 vcc, v128, v134
	v_add_u32_e32 v128, 6, v210
	v_cmp_gt_i32_e64 s[6:7], s91, v128
	v_cvt_f32_i32_e32 v150, v128
	v_add_u32_e32 v128, -5, v211
	s_and_b64 s[14:15], vcc, s[6:7]
	v_cmp_le_i32_e32 vcc, v128, v134
	v_add_u32_e32 v128, 5, v210
	v_cmp_gt_i32_e64 s[6:7], s91, v128
	v_cvt_f32_i32_e32 v158, v128
	v_add_u32_e32 v128, -4, v211
	s_and_b64 s[16:17], vcc, s[6:7]
	v_cmp_le_i32_e32 vcc, v128, v134
	v_add_u32_e32 v128, 4, v210
	v_cmp_gt_i32_e64 s[6:7], s91, v128
	v_cvt_f32_i32_e32 v212, v128
	v_add_u32_e32 v128, -3, v211
	s_and_b64 s[18:19], vcc, s[6:7]
	v_cmp_le_i32_e32 vcc, v128, v134
	v_add_u32_e32 v128, 3, v210
	v_cmp_gt_i32_e64 s[6:7], s91, v128
	v_cvt_f32_i32_e32 v148, v128
	v_add_u32_e32 v128, -2, v211
	s_and_b64 s[10:11], vcc, s[6:7]
	v_cmp_le_i32_e32 vcc, v128, v134
	v_add_u32_e32 v128, 2, v210
	v_cmp_gt_i32_e64 s[6:7], s91, v128
	v_cvt_f32_i32_e32 v154, v128
	v_add_u32_e32 v128, -1, v211
	s_and_b64 s[8:9], vcc, s[6:7]
	v_cmp_le_i32_e32 vcc, v128, v134
	v_add_u32_e32 v128, 1, v210
	v_cvt_f32_i32_e32 v146, v129
	v_cmp_gt_i32_e64 s[6:7], s91, v128
	v_cvt_f32_i32_e32 v152, v128
	v_cvt_f32_i32_e32 v132, v210
	s_and_b64 s[6:7], vcc, s[6:7]
	v_cmp_le_i32_e32 vcc, v211, v134
	v_cmp_gt_i32_e64 s[20:21], s91, v210
	s_and_b64 vcc, vcc, s[20:21]
	s_add_i32 s0, s0, 1
	v_subrev_u32_e32 v210, 32, v210
	v_add_u32_e32 v211, 32, v211
	v_lshl_add_u64 v[144:145], v[144:145], 0, s[52:53]
	s_cmp_lt_u32 s0, s71
	s_waitcnt lgkmcnt(0)
	s_mov_b32 m0, s98
	s_nop 0
	global_load_lds_dwordx4 v[250:251], off
	global_load_lds_dwordx4 v[250:251], off offset:1024
	global_load_lds_dwordx4 v[250:251], off offset:2048
	global_load_lds_dwordx4 v[250:251], off offset:3072
	s_mov_b32 m0, s99
	s_nop 0
	global_load_lds_dwordx4 v[248:249], off
	global_load_lds_dwordx4 v[248:249], off offset:1024
	global_load_lds_dwordx4 v[248:249], off offset:2048
	global_load_lds_dwordx4 v[248:249], off offset:3072
	v_mfma_f32_16x16x32_bf16 v[128:131], v[120:123], v[0:3], v[244:247]
	v_mfma_f32_16x16x32_bf16 v[128:131], v[124:127], v[4:7], v[128:131]
	v_mfma_f32_16x16x32_bf16 v[214:217], v[120:123], v[8:11], v[244:247]
	v_mfma_f32_16x16x32_bf16 v[214:217], v[124:127], v[12:15], v[214:217]
	s_nop 5
	v_fma_f32 v128, -v170, v146, v128
	v_exp_f32_e32 v147, v128
	v_fma_f32 v128, -v170, v150, v129
	v_exp_f32_e32 v149, v128
	v_cndmask_b32_e64 v157, 0, v147, s[12:13]
	v_fma_f32 v147, -v171, v146, v214
	v_exp_f32_e32 v147, v147
	v_fma_f32 v128, -v170, v158, v130
	v_exp_f32_e32 v151, v128
	v_cndmask_b32_e64 v156, 0, v147, s[12:13]
	v_fma_f32 v147, -v171, v150, v215
	v_exp_f32_e32 v147, v147
	v_fma_f32 v128, -v170, v212, v131
	v_exp_f32_e32 v153, v128
	v_cndmask_b32_e64 v160, 0, v147, s[14:15]
	v_fma_f32 v147, -v171, v158, v216
	v_exp_f32_e32 v147, v147
	v_cndmask_b32_e64 v161, 0, v149, s[14:15]
	v_add_f32_e32 v230, 0, v156
	v_add_f32_e32 v231, 0, v157
	v_cndmask_b32_e64 v219, 0, v151, s[16:17]
	v_cndmask_b32_e64 v218, 0, v147, s[16:17]
	v_fma_f32 v147, -v171, v212, v217
	v_exp_f32_e32 v147, v147
	v_add_f32_e32 v214, v160, v230
	v_add_f32_e32 v215, v161, v231
	v_cndmask_b32_e64 v221, 0, v153, s[18:19]
	v_add_f32_e32 v214, v218, v214
	v_add_f32_e32 v215, v219, v215
	v_cndmask_b32_e64 v220, 0, v147, s[18:19]
	v_add_f32_e32 v230, v220, v214
	v_add_f32_e32 v231, v221, v215
	v_mfma_f32_16x16x32_bf16 v[214:217], v[116:119], v[8:11], v[244:247]
	v_mfma_f32_16x16x32_bf16 v[214:217], v[112:115], v[12:15], v[214:217]
	v_mfma_f32_16x16x32_bf16 v[128:131], v[116:119], v[0:3], v[244:247]
	v_mfma_f32_16x16x32_bf16 v[128:131], v[112:115], v[4:7], v[128:131]
	s_nop 5
	v_fma_f32 v147, -v171, v148, v214
	v_exp_f32_e32 v147, v147
	s_nop 0
	v_cndmask_b32_e64 v222, 0, v147, s[10:11]
	v_fma_f32 v147, -v171, v154, v215
	v_exp_f32_e32 v147, v147
	s_nop 0
	v_cndmask_b32_e64 v224, 0, v147, s[8:9]
	v_fma_f32 v147, -v171, v152, v216
	v_exp_f32_e32 v147, v147
	v_fma_f32 v128, -v170, v148, v128
	v_fma_f32 v129, -v170, v154, v129
	v_fma_f32 v130, -v170, v152, v130
	v_fma_f32 v131, -v170, v132, v131
	v_cndmask_b32_e64 v226, 0, v147, s[6:7]
	v_exp_f32_e32 v128, v128
	v_exp_f32_e32 v129, v129
	v_exp_f32_e32 v130, v130
	v_exp_f32_e32 v131, v131
	v_fma_f32 v147, -v171, v132, v217
	v_exp_f32_e32 v147, v147
	v_cndmask_b32_e64 v223, 0, v128, s[10:11]
	v_cndmask_b32_e64 v225, 0, v129, s[8:9]
	v_cndmask_b32_e64 v227, 0, v130, s[6:7]
	v_cndmask_b32_e32 v229, 0, v131, vcc
	v_cvt_pk_bf16_f32 v128, v157, v161
	v_cvt_pk_bf16_f32 v129, v219, v221
	v_cvt_pk_bf16_f32 v130, v223, v225
	v_cvt_pk_bf16_f32 v131, v227, v229
	v_cndmask_b32_e32 v228, 0, v147, vcc
	s_nop 0
	v_mfma_f32_16x16x32_bf16 v[80:83], v[96:99], v[128:131], v[80:83]
	v_add_f32_e64 v230, v222, v230
	v_add_f32_e64 v231, v223, v231
	v_add_f32_e32 v214, v224, v230
	v_add_f32_e32 v215, v225, v231
	v_mfma_f32_16x16x32_bf16 v[84:87], v[100:103], v[128:131], v[84:87]
	v_add_f32_e64 v214, v226, v214
	v_add_f32_e64 v215, v227, v215
	v_add_f32_e32 v214, v228, v214
	v_add_f32_e32 v215, v229, v215
	v_mfma_f32_16x16x32_bf16 v[88:91], v[104:107], v[128:131], v[88:91]
	v_add_f32_e64 v138, v138, v214
	v_add_f32_e64 v139, v139, v215
	v_mfma_f32_16x16x32_bf16 v[92:95], v[108:111], v[128:131], v[92:95]
	v_cvt_pk_bf16_f32 v128, v156, v160
	v_cvt_pk_bf16_f32 v129, v218, v220
	v_cvt_pk_bf16_f32 v130, v222, v224
	v_cvt_pk_bf16_f32 v131, v226, v228
	s_nop 0
	s_nop 0
	v_mfma_f32_16x16x32_bf16 v[64:67], v[96:99], v[128:131], v[64:67]
	v_mfma_f32_16x16x32_bf16 v[68:71], v[100:103], v[128:131], v[68:71]
	v_mfma_f32_16x16x32_bf16 v[72:75], v[104:107], v[128:131], v[72:75]
	v_mfma_f32_16x16x32_bf16 v[76:79], v[108:111], v[128:131], v[76:79]
	v_mfma_f32_16x16x32_bf16 v[128:131], v[120:123], v[16:19], v[244:247]
	v_mfma_f32_16x16x32_bf16 v[128:131], v[124:127], v[20:23], v[128:131]
	v_mfma_f32_16x16x32_bf16 v[120:123], v[120:123], v[24:27], v[244:247]
	v_mfma_f32_16x16x32_bf16 v[120:123], v[124:127], v[28:31], v[120:123]
	s_nop 5
	v_fma_f32 v128, -v172, v146, v128
	v_exp_f32_e32 v147, v128
	v_fma_f32 v128, -v172, v150, v129
	v_exp_f32_e32 v149, v128
	v_fma_f32 v128, -v172, v158, v130
	v_exp_f32_e32 v151, v128
	v_fma_f32 v128, -v172, v212, v131
	v_exp_f32_e32 v153, v128
	v_mfma_f32_16x16x32_bf16 v[128:131], v[116:119], v[16:19], v[244:247]
	v_fma_f32 v120, -v173, v146, v120
	v_exp_f32_e32 v120, v120
	v_mfma_f32_16x16x32_bf16 v[116:119], v[116:119], v[24:27], v[244:247]
	v_fma_f32 v122, -v173, v158, v122
	v_exp_f32_e32 v122, v122
	v_mfma_f32_16x16x32_bf16 v[128:131], v[112:115], v[20:23], v[128:131]
	v_cndmask_b32_e64 v156, 0, v120, s[12:13]
	v_fma_f32 v120, -v173, v150, v121
	v_mfma_f32_16x16x32_bf16 v[112:115], v[112:115], v[28:31], v[116:119]
	v_exp_f32_e32 v120, v120
	v_cndmask_b32_e64 v146, 0, v122, s[16:17]
	s_nop 0
	v_fma_f32 v122, -v173, v212, v123
	s_nop 1
	s_nop 1
	v_fma_f32 v112, -v173, v148, v112
	v_exp_f32_e32 v112, v112
	v_fma_f32 v114, -v173, v152, v114
	v_exp_f32_e32 v114, v114
	v_fma_f32 v128, -v172, v148, v128
	v_exp_f32_e32 v122, v122
	v_cndmask_b32_e64 v148, 0, v112, s[10:11]
	v_exp_f32_e32 v128, v128
	v_fma_f32 v129, -v172, v154, v129
	v_cndmask_b32_e64 v157, 0, v147, s[12:13]
	v_fma_f32 v112, -v173, v154, v113
	v_exp_f32_e32 v129, v129
	v_fma_f32 v130, -v172, v152, v130
	v_cndmask_b32_e64 v161, 0, v149, s[14:15]
	v_add_f32_e32 v124, 0, v156
	v_add_f32_e32 v125, 0, v157
	v_cndmask_b32_e64 v160, 0, v120, s[14:15]
	v_exp_f32_e32 v112, v112
	v_cndmask_b32_e64 v152, 0, v114, s[6:7]
	v_exp_f32_e32 v130, v130
	v_fma_f32 v131, -v172, v132, v131
	v_cndmask_b32_e64 v147, 0, v151, s[16:17]
	v_add_f32_e32 v120, v160, v124
	v_add_f32_e32 v121, v161, v125
	v_fma_f32 v114, -v173, v132, v115
	v_exp_f32_e32 v131, v131
	v_cndmask_b32_e64 v151, 0, v153, s[18:19]
	v_add_f32_e32 v120, v146, v120
	v_add_f32_e32 v121, v147, v121
	v_cndmask_b32_e64 v150, 0, v122, s[18:19]
	v_exp_f32_e32 v114, v114
	v_cndmask_b32_e64 v149, 0, v128, s[10:11]
	v_add_f32_e32 v120, v150, v120
	v_add_f32_e32 v121, v151, v121
	v_cndmask_b32_e64 v155, 0, v129, s[8:9]
	v_add_f32_e32 v116, v148, v120
	v_add_f32_e32 v117, v149, v121
	v_cndmask_b32_e64 v154, 0, v112, s[8:9]
	v_cndmask_b32_e64 v153, 0, v130, s[6:7]
	v_add_f32_e32 v112, v154, v116
	v_add_f32_e32 v113, v155, v117
	v_cndmask_b32_e32 v159, 0, v131, vcc
	v_add_f32_e32 v112, v152, v112
	v_add_f32_e32 v113, v153, v113
	v_cndmask_b32_e32 v158, 0, v114, vcc
	v_add_f32_e32 v112, v158, v112
	v_add_f32_e32 v113, v159, v113
	v_cvt_pk_bf16_f32 v128, v157, v161
	v_cvt_pk_bf16_f32 v129, v147, v151
	v_cvt_pk_bf16_f32 v130, v149, v155
	v_cvt_pk_bf16_f32 v131, v153, v159
	v_cvt_pk_bf16_f32 v114, v148, v154
	s_nop 0
	v_add_f32_e32 v142, v142, v112
	v_add_f32_e32 v143, v143, v113
	v_mfma_f32_16x16x32_bf16 v[48:51], v[96:99], v[128:131], v[48:51]
	v_cvt_pk_bf16_f32 v112, v156, v160
	v_cvt_pk_bf16_f32 v113, v146, v150
	v_cvt_pk_bf16_f32 v115, v152, v158
	v_mfma_f32_16x16x32_bf16 v[52:55], v[100:103], v[128:131], v[52:55]
	v_mfma_f32_16x16x32_bf16 v[56:59], v[104:107], v[128:131], v[56:59]
	v_mfma_f32_16x16x32_bf16 v[60:63], v[108:111], v[128:131], v[60:63]
	v_mfma_f32_16x16x32_bf16 v[32:35], v[96:99], v[112:115], v[32:35]
	v_mfma_f32_16x16x32_bf16 v[36:39], v[100:103], v[112:115], v[36:39]
	v_mfma_f32_16x16x32_bf16 v[44:47], v[104:107], v[112:115], v[44:47]
	v_mfma_f32_16x16x32_bf16 v[40:43], v[108:111], v[112:115], v[40:43]
	s_cbranch_scc1 .LBB0_402
	s_branch .LBB0_369
